# P6 row-statistics exchange: only wave 0 of each workgroup polls the panel counter, the other waves wait at a workgroup barrier
# speedup vs baseline: 1.0024x; 1.0024x over previous
.LBB0_858:
	s_or_b64 exec, exec, s[38:39]
	v_lshl_add_u64 v[8:9], v[218:219], 2, s[8:9]
	global_load_dwordx4 v[4:7], v[8:9], off offset:16
	global_load_dwordx4 v[12:15], v[8:9], off
	s_waitcnt lgkmcnt(0)
	global_load_dwordx4 v[0:3], v[8:9], off offset:528
	s_nop 0
	global_load_dwordx4 v[8:11], v[8:9], off offset:512
	s_mov_b32 s27, 0x10001
	s_cmp_lg_u32 s47, 0
	s_cbranch_scc1 .Lpb_join
	s_branch .LBB0_860

.LBB0_862:
.Lpb_join:
	s_barrier
	global_load_dword v240, v[182:183], off sc1
	global_load_dword v242, v[182:183], off offset:64 sc1
	global_load_dword v244, v[182:183], off offset:128 sc1
	global_load_dword v246, v[182:183], off offset:192 sc1
	global_load_dword v248, v[182:183], off offset:512 sc1
	global_load_dword v250, v[182:183], off offset:576 sc1
	global_load_dword v252, v[182:183], off offset:640 sc1
	global_load_dword v164, v[182:183], off offset:704 sc1
	s_andn2_b64 vcc, exec, s[4:5]
	s_mov_b64 s[4:5], -1
	v_lshlrev_b64 v[70:71], 12, v[216:217]
	v_lshlrev_b64 v[68:69], 2, v[218:219]
	v_lshl_add_u64 v[70:71], s[10:11], 0, v[70:71]
	v_lshl_add_u64 v[70:71], v[70:71], 0, v[68:69]
	v_mbcnt_lo_u32_b32 v101, -1, 0
	v_mbcnt_hi_u32_b32 v101, -1, v101
	v_readfirstlane_b32 s82, v70
	v_readfirstlane_b32 s83, v71
	s_lshl_b32 s86, s47, 1
	s_add_i32 s86, s86, 0x20000
	v_and_b32_e32 v102, 15, v101
	v_lshrrev_b32_e32 v103, 4, v101
	v_lshlrev_b32_e32 v103, 1, v103
	v_and_b32_e32 v96, 7, v102
	v_xor_b32_e32 v96, v96, v103
	v_xor_b32_e32 v97, 1, v96
	v_lshlrev_b32_e32 v96, 4, v96
	v_lshlrev_b32_e32 v97, 4, v97
	v_lshl_add_u32 v96, v102, 7, v96
	v_lshl_add_u32 v97, v102, 7, v97
	v_add_u32_e32 v96, s86, v96
	v_add_u32_e32 v97, s86, v97
	v_lshrrev_b32_e32 v102, 3, v101
	v_and_b32_e32 v103, 7, v101
	v_xor_b32_e32 v98, v103, v102
	v_lshlrev_b32_e32 v98, 4, v98
	v_lshl_add_u32 v98, v102, 7, v98
	v_add_u32_e32 v98, s86, v98
	v_lshlrev_b32_e32 v99, 4, v103
	v_lshl_add_u32 v99, v102, 12, v99
	v_add_u32_e32 v100, 0x8000, v99
	s_waitcnt vmcnt(0)
	v_fmamk_f32 v240, v240, 0x3a800000, v239
	v_fmamk_f32 v242, v242, 0x3a800000, v239
	v_fmamk_f32 v244, v244, 0x3a800000, v239
	v_fmamk_f32 v246, v246, 0x3a800000, v239
	v_fmamk_f32 v248, v248, 0x3a800000, v239
	v_fmamk_f32 v250, v250, 0x3a800000, v239
	v_fmamk_f32 v252, v252, 0x3a800000, v239
	v_fmamk_f32 v164, v164, 0x3a800000, v239
	v_rsq_f32_e32 v240, v240
	v_rsq_f32_e32 v242, v242
	v_rsq_f32_e32 v244, v244
	v_rsq_f32_e32 v246, v246
	v_rsq_f32_e32 v248, v248
	v_rsq_f32_e32 v250, v250
	v_rsq_f32_e32 v252, v252
	v_rsq_f32_e32 v164, v164
	s_nop 0
	v_pk_mul_f32 v[68:69], v[220:221], v[240:241] op_sel_hi:[1,0]
	v_pk_mul_f32 v[70:71], v[184:185], v[240:241] op_sel_hi:[1,0]
	v_pk_mul_f32 v[112:113], v[12:13], v[68:69]
	v_pk_mul_f32 v[114:115], v[14:15], v[70:71]
	v_pk_mul_f32 v[156:157], v[222:223], v[240:241] op_sel_hi:[1,0]
	v_pk_mul_f32 v[158:159], v[186:187], v[240:241] op_sel_hi:[1,0]
	v_pk_mul_f32 v[116:117], v[4:5], v[156:157]
	v_pk_mul_f32 v[118:119], v[6:7], v[158:159]
	ds_write_b128 v96, v[112:115]
	ds_write_b128 v97, v[116:119]
	ds_read_b128 v[128:131], v98
	ds_read_b128 v[132:135], v98 offset:1024
	v_pk_mul_f32 v[68:69], v[188:189], v[240:241] op_sel_hi:[1,0]
	v_pk_mul_f32 v[70:71], v[176:177], v[240:241] op_sel_hi:[1,0]
	v_pk_mul_f32 v[120:121], v[8:9], v[68:69]
	v_pk_mul_f32 v[122:123], v[10:11], v[70:71]
	v_pk_mul_f32 v[156:157], v[190:191], v[240:241] op_sel_hi:[1,0]
	v_pk_mul_f32 v[158:159], v[178:179], v[240:241] op_sel_hi:[1,0]
	v_pk_mul_f32 v[124:125], v[0:1], v[156:157]
	v_pk_mul_f32 v[126:127], v[2:3], v[158:159]
	s_waitcnt lgkmcnt(0)
	s_mov_b32 s84, s82
	s_mov_b32 s85, s83
	global_store_dwordx4 v99, v[128:131], s[84:85]
	global_store_dwordx4 v100, v[132:135], s[84:85]
	ds_write_b128 v96, v[120:123]
	ds_write_b128 v97, v[124:127]
	ds_read_b128 v[84:87], v98
	ds_read_b128 v[92:95], v98 offset:1024
	v_pk_mul_f32 v[68:69], v[224:225], v[242:243] op_sel_hi:[1,0]
	v_pk_mul_f32 v[70:71], v[168:169], v[242:243] op_sel_hi:[1,0]
	v_pk_mul_f32 v[112:113], v[12:13], v[68:69]
	v_pk_mul_f32 v[114:115], v[14:15], v[70:71]
	v_pk_mul_f32 v[156:157], v[226:227], v[242:243] op_sel_hi:[1,0]
	v_pk_mul_f32 v[158:159], v[170:171], v[242:243] op_sel_hi:[1,0]
	v_pk_mul_f32 v[116:117], v[4:5], v[156:157]
	v_pk_mul_f32 v[118:119], v[6:7], v[158:159]
	s_waitcnt lgkmcnt(0)
	global_store_dwordx4 v99, v[84:87], s[84:85] offset:512
	global_store_dwordx4 v100, v[92:95], s[84:85] offset:512
	ds_write_b128 v96, v[112:115]
	ds_write_b128 v97, v[116:119]
	ds_read_b128 v[128:131], v98
	ds_read_b128 v[132:135], v98 offset:1024
	v_pk_mul_f32 v[68:69], v[172:173], v[242:243] op_sel_hi:[1,0]
	v_pk_mul_f32 v[70:71], v[160:161], v[242:243] op_sel_hi:[1,0]
	v_pk_mul_f32 v[120:121], v[8:9], v[68:69]
	v_pk_mul_f32 v[122:123], v[10:11], v[70:71]
	v_pk_mul_f32 v[156:157], v[174:175], v[242:243] op_sel_hi:[1,0]
	v_pk_mul_f32 v[158:159], v[162:163], v[242:243] op_sel_hi:[1,0]
	v_pk_mul_f32 v[124:125], v[0:1], v[156:157]
	v_pk_mul_f32 v[126:127], v[2:3], v[158:159]
	s_waitcnt lgkmcnt(0)
	s_add_u32 s84, s82, 0x10000
	s_addc_u32 s85, s83, 0
	global_store_dwordx4 v99, v[128:131], s[84:85]
	global_store_dwordx4 v100, v[132:135], s[84:85]
	ds_write_b128 v96, v[120:123]
	ds_write_b128 v97, v[124:127]
	ds_read_b128 v[84:87], v98
	ds_read_b128 v[92:95], v98 offset:1024
	v_pk_mul_f32 v[68:69], v[166:167], v[244:245] op_sel_hi:[1,0]
	v_pk_mul_f32 v[70:71], v[148:149], v[244:245] op_sel_hi:[1,0]
	v_pk_mul_f32 v[112:113], v[12:13], v[68:69]
	v_pk_mul_f32 v[114:115], v[14:15], v[70:71]
	v_pk_mul_f32 v[156:157], v[228:229], v[244:245] op_sel_hi:[1,0]
	v_pk_mul_f32 v[158:159], v[150:151], v[244:245] op_sel_hi:[1,0]
	v_pk_mul_f32 v[116:117], v[4:5], v[156:157]
	v_pk_mul_f32 v[118:119], v[6:7], v[158:159]
	s_waitcnt lgkmcnt(0)
	global_store_dwordx4 v99, v[84:87], s[84:85] offset:512
	global_store_dwordx4 v100, v[92:95], s[84:85] offset:512
	ds_write_b128 v96, v[112:115]
	ds_write_b128 v97, v[116:119]
	ds_read_b128 v[128:131], v98
	ds_read_b128 v[132:135], v98 offset:1024
	v_pk_mul_f32 v[68:69], v[152:153], v[244:245] op_sel_hi:[1,0]
	v_pk_mul_f32 v[70:71], v[136:137], v[244:245] op_sel_hi:[1,0]
	v_pk_mul_f32 v[120:121], v[8:9], v[68:69]
	v_pk_mul_f32 v[122:123], v[10:11], v[70:71]
	v_pk_mul_f32 v[156:157], v[154:155], v[244:245] op_sel_hi:[1,0]
	v_pk_mul_f32 v[158:159], v[138:139], v[244:245] op_sel_hi:[1,0]
	v_pk_mul_f32 v[124:125], v[0:1], v[156:157]
	v_pk_mul_f32 v[126:127], v[2:3], v[158:159]
	s_waitcnt lgkmcnt(0)
	s_add_u32 s84, s82, 0x20000
	s_addc_u32 s85, s83, 0
	global_store_dwordx4 v99, v[128:131], s[84:85]
	global_store_dwordx4 v100, v[132:135], s[84:85]
	ds_write_b128 v96, v[120:123]
	ds_write_b128 v97, v[124:127]
	ds_read_b128 v[84:87], v98
	ds_read_b128 v[92:95], v98 offset:1024
	v_pk_mul_f32 v[68:69], v[142:143], v[246:247] op_sel_hi:[1,0]
	v_pk_mul_f32 v[70:71], v[104:105], v[246:247] op_sel_hi:[1,0]
	v_pk_mul_f32 v[112:113], v[12:13], v[68:69]
	v_pk_mul_f32 v[114:115], v[14:15], v[70:71]
	v_pk_mul_f32 v[156:157], v[230:231], v[246:247] op_sel_hi:[1,0]
	v_pk_mul_f32 v[158:159], v[106:107], v[246:247] op_sel_hi:[1,0]
	v_pk_mul_f32 v[116:117], v[4:5], v[156:157]
	v_pk_mul_f32 v[118:119], v[6:7], v[158:159]
	s_waitcnt lgkmcnt(0)
	global_store_dwordx4 v99, v[84:87], s[84:85] offset:512
	global_store_dwordx4 v100, v[92:95], s[84:85] offset:512
	ds_write_b128 v96, v[112:115]
	ds_write_b128 v97, v[116:119]
	ds_read_b128 v[128:131], v98
	ds_read_b128 v[132:135], v98 offset:1024
	v_pk_mul_f32 v[68:69], v[108:109], v[246:247] op_sel_hi:[1,0]
	v_pk_mul_f32 v[70:71], v[88:89], v[246:247] op_sel_hi:[1,0]
	v_pk_mul_f32 v[120:121], v[8:9], v[68:69]
	v_pk_mul_f32 v[122:123], v[10:11], v[70:71]
	v_pk_mul_f32 v[156:157], v[110:111], v[246:247] op_sel_hi:[1,0]
	v_pk_mul_f32 v[158:159], v[90:91], v[246:247] op_sel_hi:[1,0]
	v_pk_mul_f32 v[124:125], v[0:1], v[156:157]
	v_pk_mul_f32 v[126:127], v[2:3], v[158:159]
	s_waitcnt lgkmcnt(0)
	s_add_u32 s84, s82, 0x30000
	s_addc_u32 s85, s83, 0
	global_store_dwordx4 v99, v[128:131], s[84:85]
	global_store_dwordx4 v100, v[132:135], s[84:85]
	ds_write_b128 v96, v[120:123]
	ds_write_b128 v97, v[124:127]
	ds_read_b128 v[84:87], v98
	ds_read_b128 v[92:95], v98 offset:1024
	v_pk_mul_f32 v[68:69], v[56:57], v[248:249] op_sel_hi:[1,0]
	v_pk_mul_f32 v[70:71], v[58:59], v[248:249] op_sel_hi:[1,0]
	v_pk_mul_f32 v[112:113], v[12:13], v[68:69]
	v_pk_mul_f32 v[114:115], v[14:15], v[70:71]
	v_pk_mul_f32 v[156:157], v[60:61], v[248:249] op_sel_hi:[1,0]
	v_pk_mul_f32 v[158:159], v[62:63], v[248:249] op_sel_hi:[1,0]
	v_pk_mul_f32 v[116:117], v[4:5], v[156:157]
	v_pk_mul_f32 v[118:119], v[6:7], v[158:159]
	s_waitcnt lgkmcnt(0)
	global_store_dwordx4 v99, v[84:87], s[84:85] offset:512
	global_store_dwordx4 v100, v[92:95], s[84:85] offset:512
	ds_write_b128 v96, v[112:115]
	ds_write_b128 v97, v[116:119]
	ds_read_b128 v[128:131], v98
	ds_read_b128 v[132:135], v98 offset:1024
	v_pk_mul_f32 v[68:69], v[48:49], v[248:249] op_sel_hi:[1,0]
	v_pk_mul_f32 v[70:71], v[50:51], v[248:249] op_sel_hi:[1,0]
	v_pk_mul_f32 v[120:121], v[8:9], v[68:69]
	v_pk_mul_f32 v[122:123], v[10:11], v[70:71]
	v_pk_mul_f32 v[156:157], v[52:53], v[248:249] op_sel_hi:[1,0]
	v_pk_mul_f32 v[158:159], v[54:55], v[248:249] op_sel_hi:[1,0]
	v_pk_mul_f32 v[124:125], v[0:1], v[156:157]
	v_pk_mul_f32 v[126:127], v[2:3], v[158:159]
	s_waitcnt lgkmcnt(0)
	s_add_u32 s84, s82, 0x80000
	s_addc_u32 s85, s83, 0
	global_store_dwordx4 v99, v[128:131], s[84:85]
	global_store_dwordx4 v100, v[132:135], s[84:85]
	ds_write_b128 v96, v[120:123]
	ds_write_b128 v97, v[124:127]
	ds_read_b128 v[84:87], v98
	ds_read_b128 v[92:95], v98 offset:1024
	v_pk_mul_f32 v[68:69], v[40:41], v[250:251] op_sel_hi:[1,0]
	v_pk_mul_f32 v[70:71], v[42:43], v[250:251] op_sel_hi:[1,0]
	v_pk_mul_f32 v[112:113], v[12:13], v[68:69]
	v_pk_mul_f32 v[114:115], v[14:15], v[70:71]
	v_pk_mul_f32 v[156:157], v[44:45], v[250:251] op_sel_hi:[1,0]
	v_pk_mul_f32 v[158:159], v[46:47], v[250:251] op_sel_hi:[1,0]
	v_pk_mul_f32 v[116:117], v[4:5], v[156:157]
	v_pk_mul_f32 v[118:119], v[6:7], v[158:159]
	s_waitcnt lgkmcnt(0)
	global_store_dwordx4 v99, v[84:87], s[84:85] offset:512
	global_store_dwordx4 v100, v[92:95], s[84:85] offset:512
	ds_write_b128 v96, v[112:115]
	ds_write_b128 v97, v[116:119]
	ds_read_b128 v[128:131], v98
	ds_read_b128 v[132:135], v98 offset:1024
	v_pk_mul_f32 v[68:69], v[32:33], v[250:251] op_sel_hi:[1,0]
	v_pk_mul_f32 v[70:71], v[34:35], v[250:251] op_sel_hi:[1,0]
	v_pk_mul_f32 v[120:121], v[8:9], v[68:69]
	v_pk_mul_f32 v[122:123], v[10:11], v[70:71]
	v_pk_mul_f32 v[156:157], v[36:37], v[250:251] op_sel_hi:[1,0]
	v_pk_mul_f32 v[158:159], v[38:39], v[250:251] op_sel_hi:[1,0]
	v_pk_mul_f32 v[124:125], v[0:1], v[156:157]
	v_pk_mul_f32 v[126:127], v[2:3], v[158:159]
	s_waitcnt lgkmcnt(0)
	s_add_u32 s84, s82, 0x90000
	s_addc_u32 s85, s83, 0
	global_store_dwordx4 v99, v[128:131], s[84:85]
	global_store_dwordx4 v100, v[132:135], s[84:85]
	ds_write_b128 v96, v[120:123]
	ds_write_b128 v97, v[124:127]
	ds_read_b128 v[84:87], v98
	ds_read_b128 v[92:95], v98 offset:1024
	v_pk_mul_f32 v[68:69], v[24:25], v[252:253] op_sel_hi:[1,0]
	v_pk_mul_f32 v[70:71], v[26:27], v[252:253] op_sel_hi:[1,0]
	v_pk_mul_f32 v[112:113], v[12:13], v[68:69]
	v_pk_mul_f32 v[114:115], v[14:15], v[70:71]
	v_pk_mul_f32 v[156:157], v[28:29], v[252:253] op_sel_hi:[1,0]
	v_pk_mul_f32 v[158:159], v[30:31], v[252:253] op_sel_hi:[1,0]
	v_pk_mul_f32 v[116:117], v[4:5], v[156:157]
	v_pk_mul_f32 v[118:119], v[6:7], v[158:159]
	s_waitcnt lgkmcnt(0)
	global_store_dwordx4 v99, v[84:87], s[84:85] offset:512
	global_store_dwordx4 v100, v[92:95], s[84:85] offset:512
	ds_write_b128 v96, v[112:115]
	ds_write_b128 v97, v[116:119]
	ds_read_b128 v[128:131], v98
	ds_read_b128 v[132:135], v98 offset:1024
	v_pk_mul_f32 v[68:69], v[16:17], v[252:253] op_sel_hi:[1,0]
	v_pk_mul_f32 v[70:71], v[18:19], v[252:253] op_sel_hi:[1,0]
	v_pk_mul_f32 v[120:121], v[8:9], v[68:69]
	v_pk_mul_f32 v[122:123], v[10:11], v[70:71]
	v_pk_mul_f32 v[156:157], v[20:21], v[252:253] op_sel_hi:[1,0]
	v_pk_mul_f32 v[158:159], v[22:23], v[252:253] op_sel_hi:[1,0]
	v_pk_mul_f32 v[124:125], v[0:1], v[156:157]
	v_pk_mul_f32 v[126:127], v[2:3], v[158:159]
	s_waitcnt lgkmcnt(0)
	s_add_u32 s84, s82, 0xa0000
	s_addc_u32 s85, s83, 0
	global_store_dwordx4 v99, v[128:131], s[84:85]
	global_store_dwordx4 v100, v[132:135], s[84:85]
	ds_write_b128 v96, v[120:123]
	ds_write_b128 v97, v[124:127]
	ds_read_b128 v[84:87], v98
	ds_read_b128 v[92:95], v98 offset:1024
	v_pk_mul_f32 v[68:69], v[80:81], v[164:165] op_sel_hi:[1,0]
	v_pk_mul_f32 v[70:71], v[72:73], v[164:165] op_sel_hi:[1,0]
	v_pk_mul_f32 v[112:113], v[12:13], v[68:69]
	v_pk_mul_f32 v[114:115], v[14:15], v[70:71]
	v_pk_mul_f32 v[156:157], v[82:83], v[164:165] op_sel_hi:[1,0]
	v_pk_mul_f32 v[158:159], v[74:75], v[164:165] op_sel_hi:[1,0]
	v_pk_mul_f32 v[116:117], v[4:5], v[156:157]
	v_pk_mul_f32 v[118:119], v[6:7], v[158:159]
	s_waitcnt lgkmcnt(0)
	global_store_dwordx4 v99, v[84:87], s[84:85] offset:512
	global_store_dwordx4 v100, v[92:95], s[84:85] offset:512
	ds_write_b128 v96, v[112:115]
	ds_write_b128 v97, v[116:119]
	ds_read_b128 v[128:131], v98
	ds_read_b128 v[132:135], v98 offset:1024
	v_pk_mul_f32 v[68:69], v[76:77], v[164:165] op_sel_hi:[1,0]
	v_pk_mul_f32 v[70:71], v[64:65], v[164:165] op_sel_hi:[1,0]
	v_pk_mul_f32 v[120:121], v[8:9], v[68:69]
	v_pk_mul_f32 v[122:123], v[10:11], v[70:71]
	v_pk_mul_f32 v[156:157], v[78:79], v[164:165] op_sel_hi:[1,0]
	v_pk_mul_f32 v[158:159], v[66:67], v[164:165] op_sel_hi:[1,0]
	v_pk_mul_f32 v[124:125], v[0:1], v[156:157]
	v_pk_mul_f32 v[126:127], v[2:3], v[158:159]
	s_waitcnt lgkmcnt(0)
	s_add_u32 s84, s82, 0xb0000
	s_addc_u32 s85, s83, 0
	global_store_dwordx4 v99, v[128:131], s[84:85]
	global_store_dwordx4 v100, v[132:135], s[84:85]
	ds_write_b128 v96, v[120:123]
	ds_write_b128 v97, v[124:127]
	ds_read_b128 v[84:87], v98
	ds_read_b128 v[92:95], v98 offset:1024
	s_waitcnt lgkmcnt(0)
	global_store_dwordx4 v99, v[84:87], s[84:85] offset:512
	global_store_dwordx4 v100, v[92:95], s[84:85] offset:512
	s_cbranch_vccnz .LBB0_828
	s_andn2_b64 vcc, exec, s[14:15]
	s_cbranch_vccnz .LBB0_827
	s_barrier
	s_branch .LBB0_827
